# SP1 load segments: fragment ds_reads issued first from precomputed base VGPRs, scalar pointer/select work moved behind them
# baseline (speedup 1.0000x reference)
.LBB0_358:
	v_lshlrev_b32_e32 v13, 2, v189
	v_lshl_or_b32 v194, s3, 6, v189
	v_lshl_or_b32 v12, v189, 6, v191
	s_lshl_b32 s3, s3, 13
	v_and_b32_e32 v13, 32, v13
	s_add_i32 m0, s45, 0x18000
	v_lshl_add_u64 v[0:1], v[0:1], 0, s[36:37]
	v_bitop3_b32 v12, v12, s3, v13 bitop3:0xde
	s_lshl_b32 s3, s10, 5
	s_waitcnt vmcnt(2)
	s_barrier
	global_load_lds_dwordx4 v[0:1], off
	v_lshl_add_u64 v[0:1], v[2:3], 0, s[36:37]
	s_add_i32 m0, s45, 0x1a000
	s_add_i32 s10, s45, 0x8000
	global_load_lds_dwordx4 v[0:1], off
	v_lshl_add_u64 v[0:1], v[8:9], 0, s[36:37]
	s_mov_b32 m0, s10
	s_add_i32 s11, s45, 0xa000
	global_load_lds_dwordx4 v[0:1], off
	v_lshl_add_u64 v[0:1], v[10:11], 0, s[36:37]
	s_mov_b32 m0, s11
	s_and_b32 s3, s3, 0x60
	global_load_lds_dwordx4 v[0:1], off
	s_add_i32 m0, s45, 0x1c000
	v_lshl_add_u64 v[0:1], v[4:5], 0, s[36:37]
	global_load_lds_dwordx4 v[0:1], off
	v_lshl_add_u64 v[0:1], v[6:7], 0, s[36:37]
	s_add_i32 m0, s45, 0x1e000
	s_add_i32 s13, s31, -2
	global_load_lds_dwordx4 v[0:1], off
	s_cmpk_lt_u32 s2, 0x100
	v_lshl_or_b32 v195, s3, 7, v192
	s_cselect_b64 s[74:75], -1, 0
	v_or_b32_e32 v196, s3, v190
	s_lshl_b32 s3, s82, 3
	v_cvt_f32_u32_e32 v0, s3
	s_lshr_b32 s2, s73, 3
	s_and_b32 s85, s73, 6
	s_add_i32 s58, s2, 1
	v_rcp_iflag_f32_e32 v0, v0
	s_cmp_lg_u64 s[42:43], 0
	s_cselect_b64 s[90:91], -1, 0
	s_cselect_b32 s100, s42, s88
	s_cselect_b32 s101, s43, s89
	s_sub_i32 s14, 0, s3
	v_mul_f32_e32 v0, 0x4f7ffffe, v0
	v_cvt_u32_f32_e32 v0, v0
	s_waitcnt vmcnt(6)
	v_mov_b32_e32 v157, v155
	s_mov_b32 s84, s2
	v_readfirstlane_b32 s15, v0
	s_mul_i32 s14, s14, s15
	s_mul_hi_u32 s14, s15, s14
	v_lshl_add_u64 v[164:165], s[42:43], 0, v[156:157]
	s_mov_b32 s18, 0
	s_add_i32 s33, s15, s14
	v_lshl_add_u64 v[166:167], s[8:9], 0, v[158:159]
	v_lshl_add_u64 v[168:169], s[8:9], 0, v[160:161]
	v_add_u32_e32 v157, 0, v12
	s_movk_i32 s69, 0x2000
	s_barrier
	v_lshlrev_b32_e32 v248, 4, v199
	v_add_u32_e32 v249, 0x10000, v195
	v_add_u32_e32 v250, 0x14000, v195
	v_add_u32_e32 v251, 0x18000, v195
	v_add_u32_e32 v252, 0x1c000, v195
	s_branch .LBB0_361

.LBB0_374:
	ds_read_b128 v[128:131], v249
	ds_read_b128 v[132:135], v249 offset:1024
	ds_read_b128 v[136:139], v249 offset:2048
	ds_read_b128 v[140:143], v249 offset:3072
	ds_read_b128 v[144:147], v250
	ds_read_b128 v[148:151], v250 offset:1024
	ds_read_b128 v[170:173], v250 offset:2048
	ds_read_b128 v[174:177], v250 offset:3072
	ds_read_b128 v[178:181], v157
	ds_read_b128 v[202:205], v157 offset:1024
	ds_read_b128 v[206:209], v157 offset:2048
	ds_read_b128 v[210:213], v157 offset:3072
	ds_read_b128 v[214:217], v157 offset:4096
	ds_read_b128 v[218:221], v157 offset:5120
	ds_read_b128 v[222:225], v157 offset:6144
	ds_read_b128 v[226:229], v157 offset:7168
	s_add_u32 s42, s46, 0x80
	s_addc_u32 s43, s47, 0
	s_add_u32 s46, s0, 0x100
	s_addc_u32 s47, s1, 0
	s_mov_b32 s0, 0
	s_add_i32 s97, s0, 2
	s_add_u32 s2, s42, 0x80
	s_addc_u32 s1, s43, 0
	s_add_i32 s12, 0, 0x10000
	s_cmp_eq_u32 s13, s0
	s_cselect_b32 s1, s95, s1
	s_cselect_b32 s0, s94, s2
	s_cselect_b32 s15, s55, s47
	s_cselect_b32 s14, s54, s46
	s_add_i32 s2, 0, 0x14000
	v_lshl_add_u64 v[230:231], s[42:43], 0, v[166:167]
	s_add_i32 m0, s45, 0xc000
	s_nop 0
	global_load_lds_dwordx4 v[230:231], off
	v_lshl_add_u64 v[230:231], s[42:43], 0, v[168:169]
	s_add_i32 m0, s45, 0xe000
	s_nop 0
	global_load_lds_dwordx4 v[230:231], off
	s_cmp_eq_u32 s18, 1
	s_cbranch_scc1 .Lpeel_strict375_1
	s_waitcnt vmcnt(16)
	s_branch .Lpeel_join375_1

.Lpeel_join375_2:
	s_waitcnt lgkmcnt(0)
	s_barrier
	s_setprio 1
	s_waitcnt lgkmcnt(0)
	v_mfma_f32_16x16x32_bf16 v[52:55], v[128:131], v[178:181], 0
	v_mfma_f32_16x16x32_bf16 v[48:51], v[136:139], v[178:181], 0
	v_mfma_f32_16x16x32_bf16 v[36:39], v[128:131], v[206:209], 0
	v_mfma_f32_16x16x32_bf16 v[32:35], v[136:139], v[206:209], 0
	v_mfma_f32_16x16x32_bf16 v[20:23], v[128:131], v[214:217], 0
	v_mfma_f32_16x16x32_bf16 v[16:19], v[136:139], v[214:217], 0
	v_mfma_f32_16x16x32_bf16 v[4:7], v[128:131], v[222:225], 0
	v_mfma_f32_16x16x32_bf16 v[0:3], v[136:139], v[222:225], 0
	v_mfma_f32_16x16x32_bf16 v[52:55], v[132:135], v[202:205], v[52:55]
	v_mfma_f32_16x16x32_bf16 v[48:51], v[140:143], v[202:205], v[48:51]
	v_mfma_f32_16x16x32_bf16 v[36:39], v[132:135], v[210:213], v[36:39]
	v_mfma_f32_16x16x32_bf16 v[32:35], v[140:143], v[210:213], v[32:35]
	v_mfma_f32_16x16x32_bf16 v[20:23], v[132:135], v[218:221], v[20:23]
	v_mfma_f32_16x16x32_bf16 v[16:19], v[140:143], v[218:221], v[16:19]
	v_mfma_f32_16x16x32_bf16 v[4:7], v[132:135], v[226:229], v[4:7]
	v_mfma_f32_16x16x32_bf16 v[0:3], v[140:143], v[226:229], v[0:3]
	v_mfma_f32_16x16x32_bf16 v[60:63], v[144:147], v[178:181], 0
	v_mfma_f32_16x16x32_bf16 v[56:59], v[170:173], v[178:181], 0
	v_mfma_f32_16x16x32_bf16 v[44:47], v[144:147], v[206:209], 0
	v_mfma_f32_16x16x32_bf16 v[40:43], v[170:173], v[206:209], 0
	v_mfma_f32_16x16x32_bf16 v[28:31], v[144:147], v[214:217], 0
	v_mfma_f32_16x16x32_bf16 v[24:27], v[170:173], v[214:217], 0
	v_mfma_f32_16x16x32_bf16 v[12:15], v[144:147], v[222:225], 0
	v_mfma_f32_16x16x32_bf16 v[8:11], v[170:173], v[222:225], 0
	v_mfma_f32_16x16x32_bf16 v[60:63], v[148:151], v[202:205], v[60:63]
	v_mfma_f32_16x16x32_bf16 v[56:59], v[174:177], v[202:205], v[56:59]
	v_mfma_f32_16x16x32_bf16 v[44:47], v[148:151], v[210:213], v[44:47]
	v_mfma_f32_16x16x32_bf16 v[40:43], v[174:177], v[210:213], v[40:43]
	v_mfma_f32_16x16x32_bf16 v[28:31], v[148:151], v[218:221], v[28:31]
	v_mfma_f32_16x16x32_bf16 v[24:27], v[174:177], v[218:221], v[24:27]
	v_mfma_f32_16x16x32_bf16 v[12:15], v[148:151], v[226:229], v[12:15]
	v_mfma_f32_16x16x32_bf16 v[8:11], v[174:177], v[226:229], v[8:11]
	s_setprio 0
	s_barrier
	ds_read_b128 v[128:131], v251
	ds_read_b128 v[132:135], v251 offset:1024
	ds_read_b128 v[136:139], v251 offset:2048
	ds_read_b128 v[140:143], v251 offset:3072
	ds_read_b128 v[144:147], v252
	ds_read_b128 v[148:151], v252 offset:1024
	ds_read_b128 v[170:173], v252 offset:2048
	ds_read_b128 v[174:177], v252 offset:3072
	ds_read_b128 v[178:181], v157 offset:32768
	ds_read_b128 v[202:205], v157 offset:33792
	ds_read_b128 v[206:209], v157 offset:34816
	ds_read_b128 v[210:213], v157 offset:35840
	ds_read_b128 v[214:217], v157 offset:36864
	ds_read_b128 v[218:221], v157 offset:37888
	ds_read_b128 v[222:225], v157 offset:38912
	ds_read_b128 v[226:229], v157 offset:39936
	s_add_i32 s2, 0, 0x18000
	s_add_i32 s12, 0, 0x1c000
	s_add_u32 s0, s0, s8
	s_addc_u32 s1, s1, s9
	s_mov_b32 m0, s28
	v_lshl_add_u64 v[242:243], s[0:1], 0, v[158:159]
	global_load_lds_dwordx4 v[242:243], off
	v_lshl_add_u64 v[242:243], s[0:1], 0, v[160:161]
	s_mov_b32 m0, s29
	s_nop 0
	global_load_lds_dwordx4 v[242:243], off
	s_waitcnt vmcnt(10)
	s_waitcnt lgkmcnt(0)
	s_barrier
	s_setprio 1
	s_waitcnt lgkmcnt(0)
	v_mfma_f32_16x16x32_bf16 v[120:123], v[128:131], v[178:181], v[120:123]
	v_mfma_f32_16x16x32_bf16 v[124:127], v[136:139], v[178:181], v[124:127]
	v_mfma_f32_16x16x32_bf16 v[100:103], v[128:131], v[206:209], v[100:103]
	v_mfma_f32_16x16x32_bf16 v[96:99], v[136:139], v[206:209], v[96:99]
	v_mfma_f32_16x16x32_bf16 v[84:87], v[128:131], v[214:217], v[84:87]
	v_mfma_f32_16x16x32_bf16 v[80:83], v[136:139], v[214:217], v[80:83]
	v_mfma_f32_16x16x32_bf16 v[68:71], v[128:131], v[222:225], v[68:71]
	v_mfma_f32_16x16x32_bf16 v[64:67], v[136:139], v[222:225], v[64:67]
	v_mfma_f32_16x16x32_bf16 v[120:123], v[132:135], v[202:205], v[120:123]
	v_mfma_f32_16x16x32_bf16 v[124:127], v[140:143], v[202:205], v[124:127]
	v_mfma_f32_16x16x32_bf16 v[100:103], v[132:135], v[210:213], v[100:103]
	v_mfma_f32_16x16x32_bf16 v[96:99], v[140:143], v[210:213], v[96:99]
	v_mfma_f32_16x16x32_bf16 v[84:87], v[132:135], v[218:221], v[84:87]
	v_mfma_f32_16x16x32_bf16 v[80:83], v[140:143], v[218:221], v[80:83]
	v_mfma_f32_16x16x32_bf16 v[68:71], v[132:135], v[226:229], v[68:71]
	v_mfma_f32_16x16x32_bf16 v[64:67], v[140:143], v[226:229], v[64:67]
	v_mfma_f32_16x16x32_bf16 v[116:119], v[144:147], v[178:181], v[116:119]
	v_mfma_f32_16x16x32_bf16 v[112:115], v[170:173], v[178:181], v[112:115]
	v_mfma_f32_16x16x32_bf16 v[108:111], v[144:147], v[206:209], v[108:111]
	v_mfma_f32_16x16x32_bf16 v[104:107], v[170:173], v[206:209], v[104:107]
	v_mfma_f32_16x16x32_bf16 v[92:95], v[144:147], v[214:217], v[92:95]
	v_mfma_f32_16x16x32_bf16 v[88:91], v[170:173], v[214:217], v[88:91]
	v_mfma_f32_16x16x32_bf16 v[76:79], v[144:147], v[222:225], v[76:79]
	v_mfma_f32_16x16x32_bf16 v[72:75], v[170:173], v[222:225], v[72:75]
	v_mfma_f32_16x16x32_bf16 v[116:119], v[148:151], v[202:205], v[116:119]
	v_mfma_f32_16x16x32_bf16 v[112:115], v[174:177], v[202:205], v[112:115]
	v_mfma_f32_16x16x32_bf16 v[108:111], v[148:151], v[210:213], v[108:111]
	v_mfma_f32_16x16x32_bf16 v[104:107], v[174:177], v[210:213], v[104:107]
	v_mfma_f32_16x16x32_bf16 v[92:95], v[148:151], v[218:221], v[92:95]
	v_mfma_f32_16x16x32_bf16 v[88:91], v[174:177], v[218:221], v[88:91]
	v_mfma_f32_16x16x32_bf16 v[76:79], v[148:151], v[226:229], v[76:79]
	v_mfma_f32_16x16x32_bf16 v[72:75], v[174:177], v[226:229], v[72:75]
	s_setprio 0
	s_barrier
	s_add_i32 s0, s2, s17
	v_lshl_add_u64 v[230:231], v[230:231], 0, s[36:37]
	s_mov_b32 m0, s0
	ds_read_b128 v[178:181], v157 offset:49152
	ds_read_b128 v[202:205], v157 offset:50176
	ds_read_b128 v[206:209], v157 offset:51200
	ds_read_b128 v[210:213], v157 offset:52224
	ds_read_b128 v[214:217], v157 offset:53248
	ds_read_b128 v[218:221], v157 offset:54272
	ds_read_b128 v[222:225], v157 offset:55296
	ds_read_b128 v[226:229], v157 offset:56320
	global_load_lds_dwordx4 v[230:231], off
	v_lshl_add_u64 v[230:231], v[232:233], 0, s[36:37]
	s_add_i32 m0, s0, 0x2000
	s_add_i32 s0, s12, s17
	global_load_lds_dwordx4 v[230:231], off
	v_lshl_add_u64 v[230:231], v[234:235], 0, s[36:37]
	s_mov_b32 m0, s0
	s_nop 0
	global_load_lds_dwordx4 v[230:231], off
	v_lshl_add_u64 v[230:231], v[236:237], 0, s[36:37]
	s_add_i32 m0, s0, 0x2000
	s_nop 0
	global_load_lds_dwordx4 v[230:231], off
	v_lshl_add_u64 v[230:231], v[238:239], 0, s[36:37]
	s_mov_b32 m0, s10
	s_nop 0
	global_load_lds_dwordx4 v[230:231], off
	v_lshl_add_u64 v[230:231], v[240:241], 0, s[36:37]
	s_mov_b32 m0, s11
	s_nop 0
	global_load_lds_dwordx4 v[230:231], off
	s_waitcnt vmcnt(10)
	s_waitcnt lgkmcnt(0)
	s_barrier
	s_setprio 1
	s_waitcnt lgkmcnt(0)
	v_mfma_f32_16x16x32_bf16 v[52:55], v[128:131], v[178:181], v[52:55]
	v_mfma_f32_16x16x32_bf16 v[48:51], v[136:139], v[178:181], v[48:51]
	v_mfma_f32_16x16x32_bf16 v[36:39], v[128:131], v[206:209], v[36:39]
	v_mfma_f32_16x16x32_bf16 v[32:35], v[136:139], v[206:209], v[32:35]
	v_mfma_f32_16x16x32_bf16 v[20:23], v[128:131], v[214:217], v[20:23]
	v_mfma_f32_16x16x32_bf16 v[16:19], v[136:139], v[214:217], v[16:19]
	v_mfma_f32_16x16x32_bf16 v[4:7], v[128:131], v[222:225], v[4:7]
	v_mfma_f32_16x16x32_bf16 v[0:3], v[136:139], v[222:225], v[0:3]
	v_mfma_f32_16x16x32_bf16 v[52:55], v[132:135], v[202:205], v[52:55]
	v_mfma_f32_16x16x32_bf16 v[48:51], v[140:143], v[202:205], v[48:51]
	v_mfma_f32_16x16x32_bf16 v[36:39], v[132:135], v[210:213], v[36:39]
	v_mfma_f32_16x16x32_bf16 v[32:35], v[140:143], v[210:213], v[32:35]
	v_mfma_f32_16x16x32_bf16 v[20:23], v[132:135], v[218:221], v[20:23]
	v_mfma_f32_16x16x32_bf16 v[16:19], v[140:143], v[218:221], v[16:19]
	v_mfma_f32_16x16x32_bf16 v[4:7], v[132:135], v[226:229], v[4:7]
	v_mfma_f32_16x16x32_bf16 v[0:3], v[140:143], v[226:229], v[0:3]
	v_mfma_f32_16x16x32_bf16 v[60:63], v[144:147], v[178:181], v[60:63]
	v_mfma_f32_16x16x32_bf16 v[56:59], v[170:173], v[178:181], v[56:59]
	v_mfma_f32_16x16x32_bf16 v[44:47], v[144:147], v[206:209], v[44:47]
	v_mfma_f32_16x16x32_bf16 v[40:43], v[170:173], v[206:209], v[40:43]
	v_mfma_f32_16x16x32_bf16 v[28:31], v[144:147], v[214:217], v[28:31]
	v_mfma_f32_16x16x32_bf16 v[24:27], v[170:173], v[214:217], v[24:27]
	v_mfma_f32_16x16x32_bf16 v[12:15], v[144:147], v[222:225], v[12:15]
	v_mfma_f32_16x16x32_bf16 v[8:11], v[170:173], v[222:225], v[8:11]
	v_mfma_f32_16x16x32_bf16 v[60:63], v[148:151], v[202:205], v[60:63]
	v_mfma_f32_16x16x32_bf16 v[56:59], v[174:177], v[202:205], v[56:59]
	v_mfma_f32_16x16x32_bf16 v[44:47], v[148:151], v[210:213], v[44:47]
	v_mfma_f32_16x16x32_bf16 v[40:43], v[174:177], v[210:213], v[40:43]
	v_mfma_f32_16x16x32_bf16 v[28:31], v[148:151], v[218:221], v[28:31]
	v_mfma_f32_16x16x32_bf16 v[24:27], v[174:177], v[218:221], v[24:27]
	v_mfma_f32_16x16x32_bf16 v[12:15], v[148:151], v[226:229], v[12:15]
	v_mfma_f32_16x16x32_bf16 v[8:11], v[174:177], v[226:229], v[8:11]
	s_setprio 0
	s_barrier
	s_add_u32 s42, s42, 0x100
	s_addc_u32 s43, s43, 0
	s_add_u32 s46, s46, 0x100
	s_addc_u32 s47, s47, 0
	s_cmp_ge_u32 s97, s31
	s_mov_b32 s0, s97
.LBB0_375:
	ds_read_b128 v[128:131], v249
	ds_read_b128 v[132:135], v249 offset:1024
	ds_read_b128 v[136:139], v249 offset:2048
	ds_read_b128 v[140:143], v249 offset:3072
	ds_read_b128 v[144:147], v250
	ds_read_b128 v[148:151], v250 offset:1024
	ds_read_b128 v[170:173], v250 offset:2048
	ds_read_b128 v[174:177], v250 offset:3072
	ds_read_b128 v[178:181], v157
	ds_read_b128 v[202:205], v157 offset:1024
	ds_read_b128 v[206:209], v157 offset:2048
	ds_read_b128 v[210:213], v157 offset:3072
	ds_read_b128 v[214:217], v157 offset:4096
	ds_read_b128 v[218:221], v157 offset:5120
	ds_read_b128 v[222:225], v157 offset:6144
	ds_read_b128 v[226:229], v157 offset:7168
	s_add_i32 s97, s0, 2
	s_add_u32 s2, s42, 0x80
	s_addc_u32 s1, s43, 0
	s_add_i32 s12, 0, 0x10000
	s_cmp_eq_u32 s13, s0
	s_cselect_b32 s1, s95, s1
	s_cselect_b32 s0, s94, s2
	s_cselect_b32 s15, s55, s47
	s_cselect_b32 s14, s54, s46
	s_add_i32 s2, 0, 0x14000
	v_lshl_add_u64 v[230:231], s[42:43], 0, v[166:167]
	s_add_i32 m0, s45, 0xc000
	s_nop 0
	global_load_lds_dwordx4 v[230:231], off
	v_lshl_add_u64 v[230:231], s[42:43], 0, v[168:169]
	s_add_i32 m0, s45, 0xe000
	s_nop 0
	global_load_lds_dwordx4 v[230:231], off
	s_waitcnt vmcnt(8)
	s_waitcnt lgkmcnt(0)
	s_barrier
	s_setprio 1
	s_waitcnt lgkmcnt(0)
	v_mfma_f32_16x16x32_bf16 v[120:123], v[128:131], v[178:181], v[120:123]
	v_mfma_f32_16x16x32_bf16 v[124:127], v[136:139], v[178:181], v[124:127]
	v_mfma_f32_16x16x32_bf16 v[100:103], v[128:131], v[206:209], v[100:103]
	v_mfma_f32_16x16x32_bf16 v[96:99], v[136:139], v[206:209], v[96:99]
	v_mfma_f32_16x16x32_bf16 v[84:87], v[128:131], v[214:217], v[84:87]
	v_mfma_f32_16x16x32_bf16 v[80:83], v[136:139], v[214:217], v[80:83]
	v_mfma_f32_16x16x32_bf16 v[68:71], v[128:131], v[222:225], v[68:71]
	v_mfma_f32_16x16x32_bf16 v[64:67], v[136:139], v[222:225], v[64:67]
	v_mfma_f32_16x16x32_bf16 v[120:123], v[132:135], v[202:205], v[120:123]
	v_mfma_f32_16x16x32_bf16 v[124:127], v[140:143], v[202:205], v[124:127]
	v_mfma_f32_16x16x32_bf16 v[100:103], v[132:135], v[210:213], v[100:103]
	v_mfma_f32_16x16x32_bf16 v[96:99], v[140:143], v[210:213], v[96:99]
	v_mfma_f32_16x16x32_bf16 v[84:87], v[132:135], v[218:221], v[84:87]
	v_mfma_f32_16x16x32_bf16 v[80:83], v[140:143], v[218:221], v[80:83]
	v_mfma_f32_16x16x32_bf16 v[68:71], v[132:135], v[226:229], v[68:71]
	v_mfma_f32_16x16x32_bf16 v[64:67], v[140:143], v[226:229], v[64:67]
	v_mfma_f32_16x16x32_bf16 v[116:119], v[144:147], v[178:181], v[116:119]
	v_mfma_f32_16x16x32_bf16 v[112:115], v[170:173], v[178:181], v[112:115]
	v_mfma_f32_16x16x32_bf16 v[108:111], v[144:147], v[206:209], v[108:111]
	v_mfma_f32_16x16x32_bf16 v[104:107], v[170:173], v[206:209], v[104:107]
	v_mfma_f32_16x16x32_bf16 v[92:95], v[144:147], v[214:217], v[92:95]
	v_mfma_f32_16x16x32_bf16 v[88:91], v[170:173], v[214:217], v[88:91]
	v_mfma_f32_16x16x32_bf16 v[76:79], v[144:147], v[222:225], v[76:79]
	v_mfma_f32_16x16x32_bf16 v[72:75], v[170:173], v[222:225], v[72:75]
	v_mfma_f32_16x16x32_bf16 v[116:119], v[148:151], v[202:205], v[116:119]
	v_mfma_f32_16x16x32_bf16 v[112:115], v[174:177], v[202:205], v[112:115]
	v_mfma_f32_16x16x32_bf16 v[108:111], v[148:151], v[210:213], v[108:111]
	v_mfma_f32_16x16x32_bf16 v[104:107], v[174:177], v[210:213], v[104:107]
	v_mfma_f32_16x16x32_bf16 v[92:95], v[148:151], v[218:221], v[92:95]
	v_mfma_f32_16x16x32_bf16 v[88:91], v[174:177], v[218:221], v[88:91]
	v_mfma_f32_16x16x32_bf16 v[76:79], v[148:151], v[226:229], v[76:79]
	v_mfma_f32_16x16x32_bf16 v[72:75], v[174:177], v[226:229], v[72:75]
	s_setprio 0
	s_barrier
	s_add_i32 s12, s12, s17
	v_lshl_add_u64 v[230:231], s[14:15], 0, v[154:155]
	s_mov_b32 m0, s12
	ds_read_b128 v[178:181], v157 offset:16384
	ds_read_b128 v[202:205], v157 offset:17408
	ds_read_b128 v[206:209], v157 offset:18432
	ds_read_b128 v[210:213], v157 offset:19456
	ds_read_b128 v[214:217], v157 offset:20480
	ds_read_b128 v[218:221], v157 offset:21504
	ds_read_b128 v[222:225], v157 offset:22528
	ds_read_b128 v[226:229], v157 offset:23552
	global_load_lds_dwordx4 v[230:231], off
	s_add_i32 m0, s12, 0x2000
	v_lshl_add_u64 v[232:233], s[14:15], 0, v[162:163]
	s_add_u32 s14, s14, s24
	s_addc_u32 s15, s15, s25
	s_add_i32 s2, s2, s17
	global_load_lds_dwordx4 v[232:233], off
	v_lshl_add_u64 v[234:235], s[14:15], 0, v[154:155]
	s_mov_b32 m0, s2
	v_lshl_add_u64 v[236:237], s[14:15], 0, v[162:163]
	global_load_lds_dwordx4 v[234:235], off
	s_add_i32 m0, s2, 0x2000
	v_lshl_add_u64 v[238:239], s[0:1], 0, v[158:159]
	global_load_lds_dwordx4 v[236:237], off
	s_mov_b32 m0, s45
	v_lshl_add_u64 v[240:241], s[0:1], 0, v[160:161]
	global_load_lds_dwordx4 v[238:239], off
	s_mov_b32 m0, s83
	s_nop 0
	global_load_lds_dwordx4 v[240:241], off
	s_waitcnt vmcnt(8)
	s_waitcnt lgkmcnt(0)
	s_barrier
	s_setprio 1
	s_waitcnt lgkmcnt(0)
	v_mfma_f32_16x16x32_bf16 v[52:55], v[128:131], v[178:181], v[52:55]
	v_mfma_f32_16x16x32_bf16 v[48:51], v[136:139], v[178:181], v[48:51]
	v_mfma_f32_16x16x32_bf16 v[36:39], v[128:131], v[206:209], v[36:39]
	v_mfma_f32_16x16x32_bf16 v[32:35], v[136:139], v[206:209], v[32:35]
	v_mfma_f32_16x16x32_bf16 v[20:23], v[128:131], v[214:217], v[20:23]
	v_mfma_f32_16x16x32_bf16 v[16:19], v[136:139], v[214:217], v[16:19]
	v_mfma_f32_16x16x32_bf16 v[4:7], v[128:131], v[222:225], v[4:7]
	v_mfma_f32_16x16x32_bf16 v[0:3], v[136:139], v[222:225], v[0:3]
	v_mfma_f32_16x16x32_bf16 v[52:55], v[132:135], v[202:205], v[52:55]
	v_mfma_f32_16x16x32_bf16 v[48:51], v[140:143], v[202:205], v[48:51]
	v_mfma_f32_16x16x32_bf16 v[36:39], v[132:135], v[210:213], v[36:39]
	v_mfma_f32_16x16x32_bf16 v[32:35], v[140:143], v[210:213], v[32:35]
	v_mfma_f32_16x16x32_bf16 v[20:23], v[132:135], v[218:221], v[20:23]
	v_mfma_f32_16x16x32_bf16 v[16:19], v[140:143], v[218:221], v[16:19]
	v_mfma_f32_16x16x32_bf16 v[4:7], v[132:135], v[226:229], v[4:7]
	v_mfma_f32_16x16x32_bf16 v[0:3], v[140:143], v[226:229], v[0:3]
	v_mfma_f32_16x16x32_bf16 v[60:63], v[144:147], v[178:181], v[60:63]
	v_mfma_f32_16x16x32_bf16 v[56:59], v[170:173], v[178:181], v[56:59]
	v_mfma_f32_16x16x32_bf16 v[44:47], v[144:147], v[206:209], v[44:47]
	v_mfma_f32_16x16x32_bf16 v[40:43], v[170:173], v[206:209], v[40:43]
	v_mfma_f32_16x16x32_bf16 v[28:31], v[144:147], v[214:217], v[28:31]
	v_mfma_f32_16x16x32_bf16 v[24:27], v[170:173], v[214:217], v[24:27]
	v_mfma_f32_16x16x32_bf16 v[12:15], v[144:147], v[222:225], v[12:15]
	v_mfma_f32_16x16x32_bf16 v[8:11], v[170:173], v[222:225], v[8:11]
	v_mfma_f32_16x16x32_bf16 v[60:63], v[148:151], v[202:205], v[60:63]
	v_mfma_f32_16x16x32_bf16 v[56:59], v[174:177], v[202:205], v[56:59]
	v_mfma_f32_16x16x32_bf16 v[44:47], v[148:151], v[210:213], v[44:47]
	v_mfma_f32_16x16x32_bf16 v[40:43], v[174:177], v[210:213], v[40:43]
	v_mfma_f32_16x16x32_bf16 v[28:31], v[148:151], v[218:221], v[28:31]
	v_mfma_f32_16x16x32_bf16 v[24:27], v[174:177], v[218:221], v[24:27]
	v_mfma_f32_16x16x32_bf16 v[12:15], v[148:151], v[226:229], v[12:15]
	v_mfma_f32_16x16x32_bf16 v[8:11], v[174:177], v[226:229], v[8:11]
	s_setprio 0
	s_barrier
	ds_read_b128 v[128:131], v251
	ds_read_b128 v[132:135], v251 offset:1024
	ds_read_b128 v[136:139], v251 offset:2048
	ds_read_b128 v[140:143], v251 offset:3072
	ds_read_b128 v[144:147], v252
	ds_read_b128 v[148:151], v252 offset:1024
	ds_read_b128 v[170:173], v252 offset:2048
	ds_read_b128 v[174:177], v252 offset:3072
	ds_read_b128 v[178:181], v157 offset:32768
	ds_read_b128 v[202:205], v157 offset:33792
	ds_read_b128 v[206:209], v157 offset:34816
	ds_read_b128 v[210:213], v157 offset:35840
	ds_read_b128 v[214:217], v157 offset:36864
	ds_read_b128 v[218:221], v157 offset:37888
	ds_read_b128 v[222:225], v157 offset:38912
	ds_read_b128 v[226:229], v157 offset:39936
	s_add_i32 s2, 0, 0x18000
	s_add_i32 s12, 0, 0x1c000
	s_add_u32 s0, s0, s8
	s_addc_u32 s1, s1, s9
	s_mov_b32 m0, s28
	v_lshl_add_u64 v[242:243], s[0:1], 0, v[158:159]
	global_load_lds_dwordx4 v[242:243], off
	v_lshl_add_u64 v[242:243], s[0:1], 0, v[160:161]
	s_mov_b32 m0, s29
	s_nop 0
	global_load_lds_dwordx4 v[242:243], off
	s_waitcnt vmcnt(8)
	s_waitcnt lgkmcnt(0)
	s_barrier
	s_setprio 1
	s_waitcnt lgkmcnt(0)
	v_mfma_f32_16x16x32_bf16 v[120:123], v[128:131], v[178:181], v[120:123]
	v_mfma_f32_16x16x32_bf16 v[124:127], v[136:139], v[178:181], v[124:127]
	v_mfma_f32_16x16x32_bf16 v[100:103], v[128:131], v[206:209], v[100:103]
	v_mfma_f32_16x16x32_bf16 v[96:99], v[136:139], v[206:209], v[96:99]
	v_mfma_f32_16x16x32_bf16 v[84:87], v[128:131], v[214:217], v[84:87]
	v_mfma_f32_16x16x32_bf16 v[80:83], v[136:139], v[214:217], v[80:83]
	v_mfma_f32_16x16x32_bf16 v[68:71], v[128:131], v[222:225], v[68:71]
	v_mfma_f32_16x16x32_bf16 v[64:67], v[136:139], v[222:225], v[64:67]
	v_mfma_f32_16x16x32_bf16 v[120:123], v[132:135], v[202:205], v[120:123]
	v_mfma_f32_16x16x32_bf16 v[124:127], v[140:143], v[202:205], v[124:127]
	v_mfma_f32_16x16x32_bf16 v[100:103], v[132:135], v[210:213], v[100:103]
	v_mfma_f32_16x16x32_bf16 v[96:99], v[140:143], v[210:213], v[96:99]
	v_mfma_f32_16x16x32_bf16 v[84:87], v[132:135], v[218:221], v[84:87]
	v_mfma_f32_16x16x32_bf16 v[80:83], v[140:143], v[218:221], v[80:83]
	v_mfma_f32_16x16x32_bf16 v[68:71], v[132:135], v[226:229], v[68:71]
	v_mfma_f32_16x16x32_bf16 v[64:67], v[140:143], v[226:229], v[64:67]
	v_mfma_f32_16x16x32_bf16 v[116:119], v[144:147], v[178:181], v[116:119]
	v_mfma_f32_16x16x32_bf16 v[112:115], v[170:173], v[178:181], v[112:115]
	v_mfma_f32_16x16x32_bf16 v[108:111], v[144:147], v[206:209], v[108:111]
	v_mfma_f32_16x16x32_bf16 v[104:107], v[170:173], v[206:209], v[104:107]
	v_mfma_f32_16x16x32_bf16 v[92:95], v[144:147], v[214:217], v[92:95]
	v_mfma_f32_16x16x32_bf16 v[88:91], v[170:173], v[214:217], v[88:91]
	v_mfma_f32_16x16x32_bf16 v[76:79], v[144:147], v[222:225], v[76:79]
	v_mfma_f32_16x16x32_bf16 v[72:75], v[170:173], v[222:225], v[72:75]
	v_mfma_f32_16x16x32_bf16 v[116:119], v[148:151], v[202:205], v[116:119]
	v_mfma_f32_16x16x32_bf16 v[112:115], v[174:177], v[202:205], v[112:115]
	v_mfma_f32_16x16x32_bf16 v[108:111], v[148:151], v[210:213], v[108:111]
	v_mfma_f32_16x16x32_bf16 v[104:107], v[174:177], v[210:213], v[104:107]
	v_mfma_f32_16x16x32_bf16 v[92:95], v[148:151], v[218:221], v[92:95]
	v_mfma_f32_16x16x32_bf16 v[88:91], v[174:177], v[218:221], v[88:91]
	v_mfma_f32_16x16x32_bf16 v[76:79], v[148:151], v[226:229], v[76:79]
	v_mfma_f32_16x16x32_bf16 v[72:75], v[174:177], v[226:229], v[72:75]
	s_setprio 0
	s_barrier
	s_add_i32 s0, s2, s17
	v_lshl_add_u64 v[230:231], v[230:231], 0, s[36:37]
	s_mov_b32 m0, s0
	ds_read_b128 v[178:181], v157 offset:49152
	ds_read_b128 v[202:205], v157 offset:50176
	ds_read_b128 v[206:209], v157 offset:51200
	ds_read_b128 v[210:213], v157 offset:52224
	ds_read_b128 v[214:217], v157 offset:53248
	ds_read_b128 v[218:221], v157 offset:54272
	ds_read_b128 v[222:225], v157 offset:55296
	ds_read_b128 v[226:229], v157 offset:56320
	global_load_lds_dwordx4 v[230:231], off
	v_lshl_add_u64 v[230:231], v[232:233], 0, s[36:37]
	s_add_i32 m0, s0, 0x2000
	s_add_i32 s0, s12, s17
	global_load_lds_dwordx4 v[230:231], off
	v_lshl_add_u64 v[230:231], v[234:235], 0, s[36:37]
	s_mov_b32 m0, s0
	s_nop 0
	global_load_lds_dwordx4 v[230:231], off
	v_lshl_add_u64 v[230:231], v[236:237], 0, s[36:37]
	s_add_i32 m0, s0, 0x2000
	s_nop 0
	global_load_lds_dwordx4 v[230:231], off
	v_lshl_add_u64 v[230:231], v[238:239], 0, s[36:37]
	s_mov_b32 m0, s10
	s_nop 0
	global_load_lds_dwordx4 v[230:231], off
	v_lshl_add_u64 v[230:231], v[240:241], 0, s[36:37]
	s_mov_b32 m0, s11
	s_nop 0
	global_load_lds_dwordx4 v[230:231], off
	s_waitcnt vmcnt(8)
	s_waitcnt lgkmcnt(0)
	s_barrier
	s_setprio 1
	s_waitcnt lgkmcnt(0)
	v_mfma_f32_16x16x32_bf16 v[52:55], v[128:131], v[178:181], v[52:55]
	v_mfma_f32_16x16x32_bf16 v[48:51], v[136:139], v[178:181], v[48:51]
	v_mfma_f32_16x16x32_bf16 v[36:39], v[128:131], v[206:209], v[36:39]
	v_mfma_f32_16x16x32_bf16 v[32:35], v[136:139], v[206:209], v[32:35]
	v_mfma_f32_16x16x32_bf16 v[20:23], v[128:131], v[214:217], v[20:23]
	v_mfma_f32_16x16x32_bf16 v[16:19], v[136:139], v[214:217], v[16:19]
	v_mfma_f32_16x16x32_bf16 v[4:7], v[128:131], v[222:225], v[4:7]
	v_mfma_f32_16x16x32_bf16 v[0:3], v[136:139], v[222:225], v[0:3]
	v_mfma_f32_16x16x32_bf16 v[52:55], v[132:135], v[202:205], v[52:55]
	v_mfma_f32_16x16x32_bf16 v[48:51], v[140:143], v[202:205], v[48:51]
	v_mfma_f32_16x16x32_bf16 v[36:39], v[132:135], v[210:213], v[36:39]
	v_mfma_f32_16x16x32_bf16 v[32:35], v[140:143], v[210:213], v[32:35]
	v_mfma_f32_16x16x32_bf16 v[20:23], v[132:135], v[218:221], v[20:23]
	v_mfma_f32_16x16x32_bf16 v[16:19], v[140:143], v[218:221], v[16:19]
	v_mfma_f32_16x16x32_bf16 v[4:7], v[132:135], v[226:229], v[4:7]
	v_mfma_f32_16x16x32_bf16 v[0:3], v[140:143], v[226:229], v[0:3]
	v_mfma_f32_16x16x32_bf16 v[60:63], v[144:147], v[178:181], v[60:63]
	v_mfma_f32_16x16x32_bf16 v[56:59], v[170:173], v[178:181], v[56:59]
	v_mfma_f32_16x16x32_bf16 v[44:47], v[144:147], v[206:209], v[44:47]
	v_mfma_f32_16x16x32_bf16 v[40:43], v[170:173], v[206:209], v[40:43]
	v_mfma_f32_16x16x32_bf16 v[28:31], v[144:147], v[214:217], v[28:31]
	v_mfma_f32_16x16x32_bf16 v[24:27], v[170:173], v[214:217], v[24:27]
	v_mfma_f32_16x16x32_bf16 v[12:15], v[144:147], v[222:225], v[12:15]
	v_mfma_f32_16x16x32_bf16 v[8:11], v[170:173], v[222:225], v[8:11]
	v_mfma_f32_16x16x32_bf16 v[60:63], v[148:151], v[202:205], v[60:63]
	v_mfma_f32_16x16x32_bf16 v[56:59], v[174:177], v[202:205], v[56:59]
	v_mfma_f32_16x16x32_bf16 v[44:47], v[148:151], v[210:213], v[44:47]
	v_mfma_f32_16x16x32_bf16 v[40:43], v[174:177], v[210:213], v[40:43]
	v_mfma_f32_16x16x32_bf16 v[28:31], v[148:151], v[218:221], v[28:31]
	v_mfma_f32_16x16x32_bf16 v[24:27], v[174:177], v[218:221], v[24:27]
	v_mfma_f32_16x16x32_bf16 v[12:15], v[148:151], v[226:229], v[12:15]
	v_mfma_f32_16x16x32_bf16 v[8:11], v[174:177], v[226:229], v[8:11]
	s_setprio 0
	s_barrier
	s_add_u32 s42, s42, 0x100
	s_addc_u32 s43, s43, 0
	s_add_u32 s46, s46, 0x100
	s_addc_u32 s47, s47, 0
	s_cmp_ge_u32 s97, s31
	s_mov_b32 s0, s97
	s_cbranch_scc0 .LBB0_375
	s_and_b64 vcc, exec, s[74:75]
	s_cbranch_vccz .LBB0_378
	s_barrier

.LBB0_465:
	s_add_i32 m0, s3, 0x18000
	v_lshl_add_u64 v[0:1], v[0:1], 0, s[36:37]
	v_lshl_or_b32 v164, s18, 6, v189
	s_lshl_b32 s14, s18, 13
	s_waitcnt vmcnt(2)
	s_barrier
	global_load_lds_dwordx4 v[0:1], off
	v_lshl_add_u64 v[0:1], v[2:3], 0, s[36:37]
	s_add_i32 m0, s3, 0x1a000
	s_add_i32 s18, s3, 0x8000
	global_load_lds_dwordx4 v[0:1], off
	v_lshl_add_u64 v[0:1], v[8:9], 0, s[36:37]
	s_mov_b32 m0, s18
	s_add_i32 s28, s3, 0xa000
	global_load_lds_dwordx4 v[0:1], off
	v_lshl_add_u64 v[0:1], v[10:11], 0, s[36:37]
	s_mov_b32 m0, s28
	s_and_b32 s17, s17, 3
	global_load_lds_dwordx4 v[0:1], off
	s_add_i32 m0, s3, 0x1c000
	v_lshl_add_u64 v[0:1], v[4:5], 0, s[36:37]
	global_load_lds_dwordx4 v[0:1], off
	v_lshl_add_u64 v[0:1], v[6:7], 0, s[36:37]
	s_add_i32 m0, s3, 0x1e000
	s_add_i32 s29, s31, -2
	global_load_lds_dwordx4 v[0:1], off
	s_cmpk_lt_u32 s23, 0x100
	s_cselect_b64 s[66:67], -1, 0
	s_lshl_b32 s16, s82, 3
	v_cvt_f32_u32_e32 v0, s16
	s_lshr_b32 s33, s73, 3
	s_and_b32 s58, s73, 6
	s_add_i32 s85, s33, 1
	v_rcp_iflag_f32_e32 v0, v0
	v_lshlrev_b32_e32 v13, 2, v189
	s_cmp_lg_u64 s[86:87], 0
	v_lshl_or_b32 v12, v189, 6, v191
	v_mul_f32_e32 v0, 0x4f7ffffe, v0
	v_cvt_u32_f32_e32 v0, v0
	v_and_b32_e32 v13, 32, v13
	s_cselect_b64 s[68:69], -1, 0
	s_cmp_lg_u64 s[50:51], 0
	v_bitop3_b32 v12, v12, s14, v13 bitop3:0xde
	s_cselect_b64 s[70:71], -1, 0
	s_sub_i32 s14, 0, s16
	v_readfirstlane_b32 s15, v0
	s_waitcnt vmcnt(6)
	s_mul_i32 s14, s14, s15
	s_mul_hi_u32 s14, s15, s14
	v_lshl_or_b32 v165, s17, 12, v192
	v_lshl_or_b32 v166, s17, 5, v190
	s_mov_b32 s92, 0
	s_add_i32 s93, s15, s14
	v_lshl_add_u64 v[142:143], s[8:9], 0, v[136:137]
	v_lshl_add_u64 v[144:145], s[8:9], 0, v[138:139]
	v_add_u32_e32 v167, 0, v12
	s_barrier
	v_add_u32_e32 v249, 0x10000, v165
	v_add_u32_e32 v250, 0x14000, v165
	v_add_u32_e32 v251, 0x18000, v165
	v_add_u32_e32 v252, 0x1c000, v165
	s_branch .LBB0_468

.LBB0_481:
	ds_read_b128 v[128:131], v249
	ds_read_b128 v[132:135], v249 offset:1024
	ds_read_b128 v[146:149], v249 offset:2048
	ds_read_b128 v[158:161], v249 offset:3072
	ds_read_b128 v[168:171], v250
	ds_read_b128 v[172:175], v250 offset:1024
	ds_read_b128 v[176:179], v250 offset:2048
	ds_read_b128 v[194:197], v250 offset:3072
	ds_read_b128 v[202:205], v167
	ds_read_b128 v[206:209], v167 offset:1024
	ds_read_b128 v[210:213], v167 offset:2048
	ds_read_b128 v[214:217], v167 offset:3072
	ds_read_b128 v[218:221], v167 offset:4096
	ds_read_b128 v[222:225], v167 offset:5120
	ds_read_b128 v[226:229], v167 offset:6144
	ds_read_b128 v[230:233], v167 offset:7168
	s_add_u32 s42, s44, 0x80
	s_addc_u32 s43, s45, 0
	s_add_u32 s44, s0, 0x100
	s_addc_u32 s45, s1, 0
	s_mov_b32 s0, 0
	s_add_i32 s47, s0, 2
	s_add_u32 s14, s42, 0x80
	s_addc_u32 s1, s43, 0
	s_add_i32 s15, 0, 0x10000
	s_cmp_eq_u32 s29, s0
	s_cselect_b32 s1, s77, s1
	s_cselect_b32 s0, s76, s14
	s_cselect_b32 s83, s79, s45
	s_cselect_b32 s82, s78, s44
	s_add_i32 s14, 0, 0x14000
	v_lshl_add_u64 v[150:151], s[42:43], 0, v[142:143]
	s_add_i32 m0, s3, 0xc000
	s_nop 0
	global_load_lds_dwordx4 v[150:151], off
	v_lshl_add_u64 v[150:151], s[42:43], 0, v[144:145]
	s_add_i32 m0, s3, 0xe000
	s_nop 0
	global_load_lds_dwordx4 v[150:151], off
	s_cmp_eq_u32 s92, 1
	s_cbranch_scc1 .Lpeel_strict482_1
	s_waitcnt vmcnt(24)
	s_branch .Lpeel_join482_1

.Lpeel_join482_2:
	s_waitcnt lgkmcnt(0)
	s_barrier
	s_setprio 1
	s_waitcnt lgkmcnt(0)
	v_mfma_f32_16x16x32_bf16 v[60:63], v[128:131], v[202:205], 0
	v_mfma_f32_16x16x32_bf16 v[56:59], v[146:149], v[202:205], 0
	v_mfma_f32_16x16x32_bf16 v[44:47], v[128:131], v[210:213], 0
	v_mfma_f32_16x16x32_bf16 v[40:43], v[146:149], v[210:213], 0
	v_mfma_f32_16x16x32_bf16 v[28:31], v[128:131], v[218:221], 0
	v_mfma_f32_16x16x32_bf16 v[24:27], v[146:149], v[218:221], 0
	v_mfma_f32_16x16x32_bf16 v[12:15], v[128:131], v[226:229], 0
	v_mfma_f32_16x16x32_bf16 v[8:11], v[146:149], v[226:229], 0
	v_mfma_f32_16x16x32_bf16 v[60:63], v[132:135], v[206:209], v[60:63]
	v_mfma_f32_16x16x32_bf16 v[56:59], v[158:161], v[206:209], v[56:59]
	v_mfma_f32_16x16x32_bf16 v[44:47], v[132:135], v[214:217], v[44:47]
	v_mfma_f32_16x16x32_bf16 v[40:43], v[158:161], v[214:217], v[40:43]
	v_mfma_f32_16x16x32_bf16 v[28:31], v[132:135], v[222:225], v[28:31]
	v_mfma_f32_16x16x32_bf16 v[24:27], v[158:161], v[222:225], v[24:27]
	v_mfma_f32_16x16x32_bf16 v[12:15], v[132:135], v[230:233], v[12:15]
	v_mfma_f32_16x16x32_bf16 v[8:11], v[158:161], v[230:233], v[8:11]
	v_mfma_f32_16x16x32_bf16 v[52:55], v[168:171], v[202:205], 0
	v_mfma_f32_16x16x32_bf16 v[48:51], v[176:179], v[202:205], 0
	v_mfma_f32_16x16x32_bf16 v[36:39], v[168:171], v[210:213], 0
	v_mfma_f32_16x16x32_bf16 v[32:35], v[176:179], v[210:213], 0
	v_mfma_f32_16x16x32_bf16 v[20:23], v[168:171], v[218:221], 0
	v_mfma_f32_16x16x32_bf16 v[16:19], v[176:179], v[218:221], 0
	v_mfma_f32_16x16x32_bf16 v[4:7], v[168:171], v[226:229], 0
	v_mfma_f32_16x16x32_bf16 v[0:3], v[176:179], v[226:229], 0
	v_mfma_f32_16x16x32_bf16 v[52:55], v[172:175], v[206:209], v[52:55]
	v_mfma_f32_16x16x32_bf16 v[48:51], v[194:197], v[206:209], v[48:51]
	v_mfma_f32_16x16x32_bf16 v[36:39], v[172:175], v[214:217], v[36:39]
	v_mfma_f32_16x16x32_bf16 v[32:35], v[194:197], v[214:217], v[32:35]
	v_mfma_f32_16x16x32_bf16 v[20:23], v[172:175], v[222:225], v[20:23]
	v_mfma_f32_16x16x32_bf16 v[16:19], v[194:197], v[222:225], v[16:19]
	v_mfma_f32_16x16x32_bf16 v[4:7], v[172:175], v[230:233], v[4:7]
	v_mfma_f32_16x16x32_bf16 v[0:3], v[194:197], v[230:233], v[0:3]
	s_setprio 0
	s_barrier
	ds_read_b128 v[128:131], v251
	ds_read_b128 v[132:135], v251 offset:1024
	ds_read_b128 v[146:149], v251 offset:2048
	ds_read_b128 v[158:161], v251 offset:3072
	ds_read_b128 v[168:171], v252
	ds_read_b128 v[172:175], v252 offset:1024
	ds_read_b128 v[176:179], v252 offset:2048
	ds_read_b128 v[194:197], v252 offset:3072
	ds_read_b128 v[202:205], v167 offset:32768
	ds_read_b128 v[206:209], v167 offset:33792
	ds_read_b128 v[210:213], v167 offset:34816
	ds_read_b128 v[214:217], v167 offset:35840
	ds_read_b128 v[218:221], v167 offset:36864
	ds_read_b128 v[222:225], v167 offset:37888
	ds_read_b128 v[226:229], v167 offset:38912
	ds_read_b128 v[230:233], v167 offset:39936
	s_add_i32 s14, 0, 0x18000
	s_add_i32 s15, 0, 0x1c000
	s_add_u32 s0, s0, s8
	s_addc_u32 s1, s1, s9
	s_mov_b32 m0, s11
	v_lshl_add_u64 v[240:241], s[0:1], 0, v[136:137]
	global_load_lds_dwordx4 v[240:241], off
	v_lshl_add_u64 v[240:241], s[0:1], 0, v[138:139]
	s_mov_b32 m0, s13
	s_nop 0
	global_load_lds_dwordx4 v[240:241], off
	s_waitcnt vmcnt(8)
	s_waitcnt lgkmcnt(0)
	s_barrier
	s_setprio 1
	s_waitcnt lgkmcnt(0)
	v_mfma_f32_16x16x32_bf16 v[124:127], v[128:131], v[202:205], v[124:127]
	v_mfma_f32_16x16x32_bf16 v[120:123], v[146:149], v[202:205], v[120:123]
	v_mfma_f32_16x16x32_bf16 v[108:111], v[128:131], v[210:213], v[108:111]
	v_mfma_f32_16x16x32_bf16 v[104:107], v[146:149], v[210:213], v[104:107]
	v_mfma_f32_16x16x32_bf16 v[92:95], v[128:131], v[218:221], v[92:95]
	v_mfma_f32_16x16x32_bf16 v[88:91], v[146:149], v[218:221], v[88:91]
	v_mfma_f32_16x16x32_bf16 v[76:79], v[128:131], v[226:229], v[76:79]
	v_mfma_f32_16x16x32_bf16 v[72:75], v[146:149], v[226:229], v[72:75]
	v_mfma_f32_16x16x32_bf16 v[124:127], v[132:135], v[206:209], v[124:127]
	v_mfma_f32_16x16x32_bf16 v[120:123], v[158:161], v[206:209], v[120:123]
	v_mfma_f32_16x16x32_bf16 v[108:111], v[132:135], v[214:217], v[108:111]
	v_mfma_f32_16x16x32_bf16 v[104:107], v[158:161], v[214:217], v[104:107]
	v_mfma_f32_16x16x32_bf16 v[92:95], v[132:135], v[222:225], v[92:95]
	v_mfma_f32_16x16x32_bf16 v[88:91], v[158:161], v[222:225], v[88:91]
	v_mfma_f32_16x16x32_bf16 v[76:79], v[132:135], v[230:233], v[76:79]
	v_mfma_f32_16x16x32_bf16 v[72:75], v[158:161], v[230:233], v[72:75]
	v_mfma_f32_16x16x32_bf16 v[116:119], v[168:171], v[202:205], v[116:119]
	v_mfma_f32_16x16x32_bf16 v[112:115], v[176:179], v[202:205], v[112:115]
	v_mfma_f32_16x16x32_bf16 v[100:103], v[168:171], v[210:213], v[100:103]
	v_mfma_f32_16x16x32_bf16 v[96:99], v[176:179], v[210:213], v[96:99]
	v_mfma_f32_16x16x32_bf16 v[84:87], v[168:171], v[218:221], v[84:87]
	v_mfma_f32_16x16x32_bf16 v[80:83], v[176:179], v[218:221], v[80:83]
	v_mfma_f32_16x16x32_bf16 v[68:71], v[168:171], v[226:229], v[68:71]
	v_mfma_f32_16x16x32_bf16 v[64:67], v[176:179], v[226:229], v[64:67]
	v_mfma_f32_16x16x32_bf16 v[116:119], v[172:175], v[206:209], v[116:119]
	v_mfma_f32_16x16x32_bf16 v[112:115], v[194:197], v[206:209], v[112:115]
	v_mfma_f32_16x16x32_bf16 v[100:103], v[172:175], v[214:217], v[100:103]
	v_mfma_f32_16x16x32_bf16 v[96:99], v[194:197], v[214:217], v[96:99]
	v_mfma_f32_16x16x32_bf16 v[84:87], v[172:175], v[222:225], v[84:87]
	v_mfma_f32_16x16x32_bf16 v[80:83], v[194:197], v[222:225], v[80:83]
	v_mfma_f32_16x16x32_bf16 v[68:71], v[172:175], v[230:233], v[68:71]
	v_mfma_f32_16x16x32_bf16 v[64:67], v[194:197], v[230:233], v[64:67]
	s_setprio 0
	s_barrier
	s_add_i32 s0, s14, s2
	v_lshl_add_u64 v[150:151], v[150:151], 0, s[36:37]
	s_mov_b32 m0, s0
	ds_read_b128 v[202:205], v167 offset:49152
	ds_read_b128 v[206:209], v167 offset:50176
	ds_read_b128 v[210:213], v167 offset:51200
	ds_read_b128 v[214:217], v167 offset:52224
	ds_read_b128 v[218:221], v167 offset:53248
	ds_read_b128 v[222:225], v167 offset:54272
	ds_read_b128 v[226:229], v167 offset:55296
	ds_read_b128 v[230:233], v167 offset:56320
	global_load_lds_dwordx4 v[150:151], off
	v_lshl_add_u64 v[150:151], v[162:163], 0, s[36:37]
	s_add_i32 m0, s0, 0x2000
	s_add_i32 s0, s15, s2
	global_load_lds_dwordx4 v[150:151], off
	v_lshl_add_u64 v[150:151], v[180:181], 0, s[36:37]
	s_mov_b32 m0, s0
	s_nop 0
	global_load_lds_dwordx4 v[150:151], off
	v_lshl_add_u64 v[150:151], v[234:235], 0, s[36:37]
	s_add_i32 m0, s0, 0x2000
	s_nop 0
	global_load_lds_dwordx4 v[150:151], off
	v_lshl_add_u64 v[150:151], v[236:237], 0, s[36:37]
	s_mov_b32 m0, s18
	s_nop 0
	global_load_lds_dwordx4 v[150:151], off
	v_lshl_add_u64 v[150:151], v[238:239], 0, s[36:37]
	s_mov_b32 m0, s28
	s_nop 0
	global_load_lds_dwordx4 v[150:151], off
	s_waitcnt vmcnt(8)
	s_waitcnt lgkmcnt(0)
	s_barrier
	s_setprio 1
	s_waitcnt lgkmcnt(0)
	v_mfma_f32_16x16x32_bf16 v[60:63], v[128:131], v[202:205], v[60:63]
	v_mfma_f32_16x16x32_bf16 v[56:59], v[146:149], v[202:205], v[56:59]
	v_mfma_f32_16x16x32_bf16 v[44:47], v[128:131], v[210:213], v[44:47]
	v_mfma_f32_16x16x32_bf16 v[40:43], v[146:149], v[210:213], v[40:43]
	v_mfma_f32_16x16x32_bf16 v[28:31], v[128:131], v[218:221], v[28:31]
	v_mfma_f32_16x16x32_bf16 v[24:27], v[146:149], v[218:221], v[24:27]
	v_mfma_f32_16x16x32_bf16 v[12:15], v[128:131], v[226:229], v[12:15]
	v_mfma_f32_16x16x32_bf16 v[8:11], v[146:149], v[226:229], v[8:11]
	v_mfma_f32_16x16x32_bf16 v[60:63], v[132:135], v[206:209], v[60:63]
	v_mfma_f32_16x16x32_bf16 v[56:59], v[158:161], v[206:209], v[56:59]
	v_mfma_f32_16x16x32_bf16 v[44:47], v[132:135], v[214:217], v[44:47]
	v_mfma_f32_16x16x32_bf16 v[40:43], v[158:161], v[214:217], v[40:43]
	v_mfma_f32_16x16x32_bf16 v[28:31], v[132:135], v[222:225], v[28:31]
	v_mfma_f32_16x16x32_bf16 v[24:27], v[158:161], v[222:225], v[24:27]
	v_mfma_f32_16x16x32_bf16 v[12:15], v[132:135], v[230:233], v[12:15]
	v_mfma_f32_16x16x32_bf16 v[8:11], v[158:161], v[230:233], v[8:11]
	v_mfma_f32_16x16x32_bf16 v[52:55], v[168:171], v[202:205], v[52:55]
	v_mfma_f32_16x16x32_bf16 v[48:51], v[176:179], v[202:205], v[48:51]
	v_mfma_f32_16x16x32_bf16 v[36:39], v[168:171], v[210:213], v[36:39]
	v_mfma_f32_16x16x32_bf16 v[32:35], v[176:179], v[210:213], v[32:35]
	v_mfma_f32_16x16x32_bf16 v[20:23], v[168:171], v[218:221], v[20:23]
	v_mfma_f32_16x16x32_bf16 v[16:19], v[176:179], v[218:221], v[16:19]
	v_mfma_f32_16x16x32_bf16 v[4:7], v[168:171], v[226:229], v[4:7]
	v_mfma_f32_16x16x32_bf16 v[0:3], v[176:179], v[226:229], v[0:3]
	v_mfma_f32_16x16x32_bf16 v[52:55], v[172:175], v[206:209], v[52:55]
	v_mfma_f32_16x16x32_bf16 v[48:51], v[194:197], v[206:209], v[48:51]
	v_mfma_f32_16x16x32_bf16 v[36:39], v[172:175], v[214:217], v[36:39]
	v_mfma_f32_16x16x32_bf16 v[32:35], v[194:197], v[214:217], v[32:35]
	v_mfma_f32_16x16x32_bf16 v[20:23], v[172:175], v[222:225], v[20:23]
	v_mfma_f32_16x16x32_bf16 v[16:19], v[194:197], v[222:225], v[16:19]
	v_mfma_f32_16x16x32_bf16 v[4:7], v[172:175], v[230:233], v[4:7]
	v_mfma_f32_16x16x32_bf16 v[0:3], v[194:197], v[230:233], v[0:3]
	s_setprio 0
	s_barrier
	s_add_u32 s42, s42, 0x100
	s_addc_u32 s43, s43, 0
	s_add_u32 s44, s44, 0x100
	s_addc_u32 s45, s45, 0
	s_cmp_ge_u32 s47, s31
	s_mov_b32 s0, s47
.LBB0_482:
	ds_read_b128 v[128:131], v249
	ds_read_b128 v[132:135], v249 offset:1024
	ds_read_b128 v[146:149], v249 offset:2048
	ds_read_b128 v[158:161], v249 offset:3072
	ds_read_b128 v[168:171], v250
	ds_read_b128 v[172:175], v250 offset:1024
	ds_read_b128 v[176:179], v250 offset:2048
	ds_read_b128 v[194:197], v250 offset:3072
	ds_read_b128 v[202:205], v167
	ds_read_b128 v[206:209], v167 offset:1024
	ds_read_b128 v[210:213], v167 offset:2048
	ds_read_b128 v[214:217], v167 offset:3072
	ds_read_b128 v[218:221], v167 offset:4096
	ds_read_b128 v[222:225], v167 offset:5120
	ds_read_b128 v[226:229], v167 offset:6144
	ds_read_b128 v[230:233], v167 offset:7168
	s_add_i32 s47, s0, 2
	s_add_u32 s14, s42, 0x80
	s_addc_u32 s1, s43, 0
	s_add_i32 s15, 0, 0x10000
	s_cmp_eq_u32 s29, s0
	s_cselect_b32 s1, s77, s1
	s_cselect_b32 s0, s76, s14
	s_cselect_b32 s83, s79, s45
	s_cselect_b32 s82, s78, s44
	s_add_i32 s14, 0, 0x14000
	v_lshl_add_u64 v[150:151], s[42:43], 0, v[142:143]
	s_add_i32 m0, s3, 0xc000
	s_nop 0
	global_load_lds_dwordx4 v[150:151], off
	v_lshl_add_u64 v[150:151], s[42:43], 0, v[144:145]
	s_add_i32 m0, s3, 0xe000
	s_nop 0
	global_load_lds_dwordx4 v[150:151], off
	s_waitcnt vmcnt(8)
	s_waitcnt lgkmcnt(0)
	s_barrier
	s_setprio 1
	s_waitcnt lgkmcnt(0)
	v_mfma_f32_16x16x32_bf16 v[124:127], v[128:131], v[202:205], v[124:127]
	v_mfma_f32_16x16x32_bf16 v[120:123], v[146:149], v[202:205], v[120:123]
	v_mfma_f32_16x16x32_bf16 v[108:111], v[128:131], v[210:213], v[108:111]
	v_mfma_f32_16x16x32_bf16 v[104:107], v[146:149], v[210:213], v[104:107]
	v_mfma_f32_16x16x32_bf16 v[92:95], v[128:131], v[218:221], v[92:95]
	v_mfma_f32_16x16x32_bf16 v[88:91], v[146:149], v[218:221], v[88:91]
	v_mfma_f32_16x16x32_bf16 v[76:79], v[128:131], v[226:229], v[76:79]
	v_mfma_f32_16x16x32_bf16 v[72:75], v[146:149], v[226:229], v[72:75]
	v_mfma_f32_16x16x32_bf16 v[124:127], v[132:135], v[206:209], v[124:127]
	v_mfma_f32_16x16x32_bf16 v[120:123], v[158:161], v[206:209], v[120:123]
	v_mfma_f32_16x16x32_bf16 v[108:111], v[132:135], v[214:217], v[108:111]
	v_mfma_f32_16x16x32_bf16 v[104:107], v[158:161], v[214:217], v[104:107]
	v_mfma_f32_16x16x32_bf16 v[92:95], v[132:135], v[222:225], v[92:95]
	v_mfma_f32_16x16x32_bf16 v[88:91], v[158:161], v[222:225], v[88:91]
	v_mfma_f32_16x16x32_bf16 v[76:79], v[132:135], v[230:233], v[76:79]
	v_mfma_f32_16x16x32_bf16 v[72:75], v[158:161], v[230:233], v[72:75]
	v_mfma_f32_16x16x32_bf16 v[116:119], v[168:171], v[202:205], v[116:119]
	v_mfma_f32_16x16x32_bf16 v[112:115], v[176:179], v[202:205], v[112:115]
	v_mfma_f32_16x16x32_bf16 v[100:103], v[168:171], v[210:213], v[100:103]
	v_mfma_f32_16x16x32_bf16 v[96:99], v[176:179], v[210:213], v[96:99]
	v_mfma_f32_16x16x32_bf16 v[84:87], v[168:171], v[218:221], v[84:87]
	v_mfma_f32_16x16x32_bf16 v[80:83], v[176:179], v[218:221], v[80:83]
	v_mfma_f32_16x16x32_bf16 v[68:71], v[168:171], v[226:229], v[68:71]
	v_mfma_f32_16x16x32_bf16 v[64:67], v[176:179], v[226:229], v[64:67]
	v_mfma_f32_16x16x32_bf16 v[116:119], v[172:175], v[206:209], v[116:119]
	v_mfma_f32_16x16x32_bf16 v[112:115], v[194:197], v[206:209], v[112:115]
	v_mfma_f32_16x16x32_bf16 v[100:103], v[172:175], v[214:217], v[100:103]
	v_mfma_f32_16x16x32_bf16 v[96:99], v[194:197], v[214:217], v[96:99]
	v_mfma_f32_16x16x32_bf16 v[84:87], v[172:175], v[222:225], v[84:87]
	v_mfma_f32_16x16x32_bf16 v[80:83], v[194:197], v[222:225], v[80:83]
	v_mfma_f32_16x16x32_bf16 v[68:71], v[172:175], v[230:233], v[68:71]
	v_mfma_f32_16x16x32_bf16 v[64:67], v[194:197], v[230:233], v[64:67]
	s_setprio 0
	s_barrier
	s_add_i32 s15, s15, s2
	v_lshl_add_u64 v[150:151], s[82:83], 0, v[154:155]
	s_mov_b32 m0, s15
	ds_read_b128 v[202:205], v167 offset:16384
	ds_read_b128 v[206:209], v167 offset:17408
	ds_read_b128 v[210:213], v167 offset:18432
	ds_read_b128 v[214:217], v167 offset:19456
	ds_read_b128 v[218:221], v167 offset:20480
	ds_read_b128 v[222:225], v167 offset:21504
	ds_read_b128 v[226:229], v167 offset:22528
	ds_read_b128 v[230:233], v167 offset:23552
	global_load_lds_dwordx4 v[150:151], off
	s_add_i32 m0, s15, 0x2000
	v_lshl_add_u64 v[162:163], s[82:83], 0, v[140:141]
	s_add_u32 s82, s82, s24
	s_addc_u32 s83, s83, s25
	s_add_i32 s14, s14, s2
	global_load_lds_dwordx4 v[162:163], off
	v_lshl_add_u64 v[180:181], s[82:83], 0, v[154:155]
	s_mov_b32 m0, s14
	v_lshl_add_u64 v[234:235], s[82:83], 0, v[140:141]
	global_load_lds_dwordx4 v[180:181], off
	s_add_i32 m0, s14, 0x2000
	v_lshl_add_u64 v[236:237], s[0:1], 0, v[136:137]
	global_load_lds_dwordx4 v[234:235], off
	s_mov_b32 m0, s3
	v_lshl_add_u64 v[238:239], s[0:1], 0, v[138:139]
	global_load_lds_dwordx4 v[236:237], off
	s_mov_b32 m0, s10
	s_nop 0
	global_load_lds_dwordx4 v[238:239], off
	s_waitcnt vmcnt(8)
	s_waitcnt lgkmcnt(0)
	s_barrier
	s_setprio 1
	s_waitcnt lgkmcnt(0)
	v_mfma_f32_16x16x32_bf16 v[60:63], v[128:131], v[202:205], v[60:63]
	v_mfma_f32_16x16x32_bf16 v[56:59], v[146:149], v[202:205], v[56:59]
	v_mfma_f32_16x16x32_bf16 v[44:47], v[128:131], v[210:213], v[44:47]
	v_mfma_f32_16x16x32_bf16 v[40:43], v[146:149], v[210:213], v[40:43]
	v_mfma_f32_16x16x32_bf16 v[28:31], v[128:131], v[218:221], v[28:31]
	v_mfma_f32_16x16x32_bf16 v[24:27], v[146:149], v[218:221], v[24:27]
	v_mfma_f32_16x16x32_bf16 v[12:15], v[128:131], v[226:229], v[12:15]
	v_mfma_f32_16x16x32_bf16 v[8:11], v[146:149], v[226:229], v[8:11]
	v_mfma_f32_16x16x32_bf16 v[60:63], v[132:135], v[206:209], v[60:63]
	v_mfma_f32_16x16x32_bf16 v[56:59], v[158:161], v[206:209], v[56:59]
	v_mfma_f32_16x16x32_bf16 v[44:47], v[132:135], v[214:217], v[44:47]
	v_mfma_f32_16x16x32_bf16 v[40:43], v[158:161], v[214:217], v[40:43]
	v_mfma_f32_16x16x32_bf16 v[28:31], v[132:135], v[222:225], v[28:31]
	v_mfma_f32_16x16x32_bf16 v[24:27], v[158:161], v[222:225], v[24:27]
	v_mfma_f32_16x16x32_bf16 v[12:15], v[132:135], v[230:233], v[12:15]
	v_mfma_f32_16x16x32_bf16 v[8:11], v[158:161], v[230:233], v[8:11]
	v_mfma_f32_16x16x32_bf16 v[52:55], v[168:171], v[202:205], v[52:55]
	v_mfma_f32_16x16x32_bf16 v[48:51], v[176:179], v[202:205], v[48:51]
	v_mfma_f32_16x16x32_bf16 v[36:39], v[168:171], v[210:213], v[36:39]
	v_mfma_f32_16x16x32_bf16 v[32:35], v[176:179], v[210:213], v[32:35]
	v_mfma_f32_16x16x32_bf16 v[20:23], v[168:171], v[218:221], v[20:23]
	v_mfma_f32_16x16x32_bf16 v[16:19], v[176:179], v[218:221], v[16:19]
	v_mfma_f32_16x16x32_bf16 v[4:7], v[168:171], v[226:229], v[4:7]
	v_mfma_f32_16x16x32_bf16 v[0:3], v[176:179], v[226:229], v[0:3]
	v_mfma_f32_16x16x32_bf16 v[52:55], v[172:175], v[206:209], v[52:55]
	v_mfma_f32_16x16x32_bf16 v[48:51], v[194:197], v[206:209], v[48:51]
	v_mfma_f32_16x16x32_bf16 v[36:39], v[172:175], v[214:217], v[36:39]
	v_mfma_f32_16x16x32_bf16 v[32:35], v[194:197], v[214:217], v[32:35]
	v_mfma_f32_16x16x32_bf16 v[20:23], v[172:175], v[222:225], v[20:23]
	v_mfma_f32_16x16x32_bf16 v[16:19], v[194:197], v[222:225], v[16:19]
	v_mfma_f32_16x16x32_bf16 v[4:7], v[172:175], v[230:233], v[4:7]
	v_mfma_f32_16x16x32_bf16 v[0:3], v[194:197], v[230:233], v[0:3]
	s_setprio 0
	s_barrier
	ds_read_b128 v[128:131], v251
	ds_read_b128 v[132:135], v251 offset:1024
	ds_read_b128 v[146:149], v251 offset:2048
	ds_read_b128 v[158:161], v251 offset:3072
	ds_read_b128 v[168:171], v252
	ds_read_b128 v[172:175], v252 offset:1024
	ds_read_b128 v[176:179], v252 offset:2048
	ds_read_b128 v[194:197], v252 offset:3072
	ds_read_b128 v[202:205], v167 offset:32768
	ds_read_b128 v[206:209], v167 offset:33792
	ds_read_b128 v[210:213], v167 offset:34816
	ds_read_b128 v[214:217], v167 offset:35840
	ds_read_b128 v[218:221], v167 offset:36864
	ds_read_b128 v[222:225], v167 offset:37888
	ds_read_b128 v[226:229], v167 offset:38912
	ds_read_b128 v[230:233], v167 offset:39936
	s_add_i32 s14, 0, 0x18000
	s_add_i32 s15, 0, 0x1c000
	s_add_u32 s0, s0, s8
	s_addc_u32 s1, s1, s9
	s_mov_b32 m0, s11
	v_lshl_add_u64 v[240:241], s[0:1], 0, v[136:137]
	global_load_lds_dwordx4 v[240:241], off
	v_lshl_add_u64 v[240:241], s[0:1], 0, v[138:139]
	s_mov_b32 m0, s13
	s_nop 0
	global_load_lds_dwordx4 v[240:241], off
	s_waitcnt vmcnt(8)
	s_waitcnt lgkmcnt(0)
	s_barrier
	s_setprio 1
	s_waitcnt lgkmcnt(0)
	v_mfma_f32_16x16x32_bf16 v[124:127], v[128:131], v[202:205], v[124:127]
	v_mfma_f32_16x16x32_bf16 v[120:123], v[146:149], v[202:205], v[120:123]
	v_mfma_f32_16x16x32_bf16 v[108:111], v[128:131], v[210:213], v[108:111]
	v_mfma_f32_16x16x32_bf16 v[104:107], v[146:149], v[210:213], v[104:107]
	v_mfma_f32_16x16x32_bf16 v[92:95], v[128:131], v[218:221], v[92:95]
	v_mfma_f32_16x16x32_bf16 v[88:91], v[146:149], v[218:221], v[88:91]
	v_mfma_f32_16x16x32_bf16 v[76:79], v[128:131], v[226:229], v[76:79]
	v_mfma_f32_16x16x32_bf16 v[72:75], v[146:149], v[226:229], v[72:75]
	v_mfma_f32_16x16x32_bf16 v[124:127], v[132:135], v[206:209], v[124:127]
	v_mfma_f32_16x16x32_bf16 v[120:123], v[158:161], v[206:209], v[120:123]
	v_mfma_f32_16x16x32_bf16 v[108:111], v[132:135], v[214:217], v[108:111]
	v_mfma_f32_16x16x32_bf16 v[104:107], v[158:161], v[214:217], v[104:107]
	v_mfma_f32_16x16x32_bf16 v[92:95], v[132:135], v[222:225], v[92:95]
	v_mfma_f32_16x16x32_bf16 v[88:91], v[158:161], v[222:225], v[88:91]
	v_mfma_f32_16x16x32_bf16 v[76:79], v[132:135], v[230:233], v[76:79]
	v_mfma_f32_16x16x32_bf16 v[72:75], v[158:161], v[230:233], v[72:75]
	v_mfma_f32_16x16x32_bf16 v[116:119], v[168:171], v[202:205], v[116:119]
	v_mfma_f32_16x16x32_bf16 v[112:115], v[176:179], v[202:205], v[112:115]
	v_mfma_f32_16x16x32_bf16 v[100:103], v[168:171], v[210:213], v[100:103]
	v_mfma_f32_16x16x32_bf16 v[96:99], v[176:179], v[210:213], v[96:99]
	v_mfma_f32_16x16x32_bf16 v[84:87], v[168:171], v[218:221], v[84:87]
	v_mfma_f32_16x16x32_bf16 v[80:83], v[176:179], v[218:221], v[80:83]
	v_mfma_f32_16x16x32_bf16 v[68:71], v[168:171], v[226:229], v[68:71]
	v_mfma_f32_16x16x32_bf16 v[64:67], v[176:179], v[226:229], v[64:67]
	v_mfma_f32_16x16x32_bf16 v[116:119], v[172:175], v[206:209], v[116:119]
	v_mfma_f32_16x16x32_bf16 v[112:115], v[194:197], v[206:209], v[112:115]
	v_mfma_f32_16x16x32_bf16 v[100:103], v[172:175], v[214:217], v[100:103]
	v_mfma_f32_16x16x32_bf16 v[96:99], v[194:197], v[214:217], v[96:99]
	v_mfma_f32_16x16x32_bf16 v[84:87], v[172:175], v[222:225], v[84:87]
	v_mfma_f32_16x16x32_bf16 v[80:83], v[194:197], v[222:225], v[80:83]
	v_mfma_f32_16x16x32_bf16 v[68:71], v[172:175], v[230:233], v[68:71]
	v_mfma_f32_16x16x32_bf16 v[64:67], v[194:197], v[230:233], v[64:67]
	s_setprio 0
	s_barrier
	s_add_i32 s0, s14, s2
	v_lshl_add_u64 v[150:151], v[150:151], 0, s[36:37]
	s_mov_b32 m0, s0
	ds_read_b128 v[202:205], v167 offset:49152
	ds_read_b128 v[206:209], v167 offset:50176
	ds_read_b128 v[210:213], v167 offset:51200
	ds_read_b128 v[214:217], v167 offset:52224
	ds_read_b128 v[218:221], v167 offset:53248
	ds_read_b128 v[222:225], v167 offset:54272
	ds_read_b128 v[226:229], v167 offset:55296
	ds_read_b128 v[230:233], v167 offset:56320
	global_load_lds_dwordx4 v[150:151], off
	v_lshl_add_u64 v[150:151], v[162:163], 0, s[36:37]
	s_add_i32 m0, s0, 0x2000
	s_add_i32 s0, s15, s2
	global_load_lds_dwordx4 v[150:151], off
	v_lshl_add_u64 v[150:151], v[180:181], 0, s[36:37]
	s_mov_b32 m0, s0
	s_nop 0
	global_load_lds_dwordx4 v[150:151], off
	v_lshl_add_u64 v[150:151], v[234:235], 0, s[36:37]
	s_add_i32 m0, s0, 0x2000
	s_nop 0
	global_load_lds_dwordx4 v[150:151], off
	v_lshl_add_u64 v[150:151], v[236:237], 0, s[36:37]
	s_mov_b32 m0, s18
	s_nop 0
	global_load_lds_dwordx4 v[150:151], off
	v_lshl_add_u64 v[150:151], v[238:239], 0, s[36:37]
	s_mov_b32 m0, s28
	s_nop 0
	global_load_lds_dwordx4 v[150:151], off
	s_waitcnt vmcnt(8)
	s_waitcnt lgkmcnt(0)
	s_barrier
	s_setprio 1
	s_waitcnt lgkmcnt(0)
	v_mfma_f32_16x16x32_bf16 v[60:63], v[128:131], v[202:205], v[60:63]
	v_mfma_f32_16x16x32_bf16 v[56:59], v[146:149], v[202:205], v[56:59]
	v_mfma_f32_16x16x32_bf16 v[44:47], v[128:131], v[210:213], v[44:47]
	v_mfma_f32_16x16x32_bf16 v[40:43], v[146:149], v[210:213], v[40:43]
	v_mfma_f32_16x16x32_bf16 v[28:31], v[128:131], v[218:221], v[28:31]
	v_mfma_f32_16x16x32_bf16 v[24:27], v[146:149], v[218:221], v[24:27]
	v_mfma_f32_16x16x32_bf16 v[12:15], v[128:131], v[226:229], v[12:15]
	v_mfma_f32_16x16x32_bf16 v[8:11], v[146:149], v[226:229], v[8:11]
	v_mfma_f32_16x16x32_bf16 v[60:63], v[132:135], v[206:209], v[60:63]
	v_mfma_f32_16x16x32_bf16 v[56:59], v[158:161], v[206:209], v[56:59]
	v_mfma_f32_16x16x32_bf16 v[44:47], v[132:135], v[214:217], v[44:47]
	v_mfma_f32_16x16x32_bf16 v[40:43], v[158:161], v[214:217], v[40:43]
	v_mfma_f32_16x16x32_bf16 v[28:31], v[132:135], v[222:225], v[28:31]
	v_mfma_f32_16x16x32_bf16 v[24:27], v[158:161], v[222:225], v[24:27]
	v_mfma_f32_16x16x32_bf16 v[12:15], v[132:135], v[230:233], v[12:15]
	v_mfma_f32_16x16x32_bf16 v[8:11], v[158:161], v[230:233], v[8:11]
	v_mfma_f32_16x16x32_bf16 v[52:55], v[168:171], v[202:205], v[52:55]
	v_mfma_f32_16x16x32_bf16 v[48:51], v[176:179], v[202:205], v[48:51]
	v_mfma_f32_16x16x32_bf16 v[36:39], v[168:171], v[210:213], v[36:39]
	v_mfma_f32_16x16x32_bf16 v[32:35], v[176:179], v[210:213], v[32:35]
	v_mfma_f32_16x16x32_bf16 v[20:23], v[168:171], v[218:221], v[20:23]
	v_mfma_f32_16x16x32_bf16 v[16:19], v[176:179], v[218:221], v[16:19]
	v_mfma_f32_16x16x32_bf16 v[4:7], v[168:171], v[226:229], v[4:7]
	v_mfma_f32_16x16x32_bf16 v[0:3], v[176:179], v[226:229], v[0:3]
	v_mfma_f32_16x16x32_bf16 v[52:55], v[172:175], v[206:209], v[52:55]
	v_mfma_f32_16x16x32_bf16 v[48:51], v[194:197], v[206:209], v[48:51]
	v_mfma_f32_16x16x32_bf16 v[36:39], v[172:175], v[214:217], v[36:39]
	v_mfma_f32_16x16x32_bf16 v[32:35], v[194:197], v[214:217], v[32:35]
	v_mfma_f32_16x16x32_bf16 v[20:23], v[172:175], v[222:225], v[20:23]
	v_mfma_f32_16x16x32_bf16 v[16:19], v[194:197], v[222:225], v[16:19]
	v_mfma_f32_16x16x32_bf16 v[4:7], v[172:175], v[230:233], v[4:7]
	v_mfma_f32_16x16x32_bf16 v[0:3], v[194:197], v[230:233], v[0:3]
	s_setprio 0
	s_barrier
	s_add_u32 s42, s42, 0x100
	s_addc_u32 s43, s43, 0
	s_add_u32 s44, s44, 0x100
	s_addc_u32 s45, s45, 0
	s_cmp_ge_u32 s47, s31
	s_mov_b32 s0, s47
	s_cbranch_scc0 .LBB0_482
	s_and_b64 vcc, exec, s[66:67]
	s_cbranch_vccz .LBB0_485
	s_barrier

	.amdhsa_kernel _Z8mega_fwd4Args
		.amdhsa_group_segment_fixed_size 0
		.amdhsa_private_segment_fixed_size 0
		.amdhsa_kernarg_size 400
		.amdhsa_user_sgpr_count 2
		.amdhsa_user_sgpr_dispatch_ptr 0
		.amdhsa_user_sgpr_queue_ptr 0
		.amdhsa_user_sgpr_kernarg_segment_ptr 1
		.amdhsa_user_sgpr_dispatch_id 0
		.amdhsa_user_sgpr_kernarg_preload_length 0
		.amdhsa_user_sgpr_kernarg_preload_offset 0
		.amdhsa_user_sgpr_private_segment_size 0
		.amdhsa_uses_dynamic_stack 0
		.amdhsa_enable_private_segment 0
		.amdhsa_system_sgpr_workgroup_id_x 1
		.amdhsa_system_sgpr_workgroup_id_y 0
		.amdhsa_system_sgpr_workgroup_id_z 0
		.amdhsa_system_sgpr_workgroup_info 0
		.amdhsa_system_vgpr_workitem_id 2
		.amdhsa_next_free_vgpr 256
		.amdhsa_next_free_sgpr 102
		.amdhsa_accum_offset 256
		.amdhsa_reserve_vcc 1
		.amdhsa_float_round_mode_32 0
		.amdhsa_float_round_mode_16_64 0
		.amdhsa_float_denorm_mode_32 3
		.amdhsa_float_denorm_mode_16_64 3
		.amdhsa_dx10_clamp 1
		.amdhsa_ieee_mode 1
		.amdhsa_fp16_overflow 0
		.amdhsa_tg_split 0
		.amdhsa_exception_fp_ieee_invalid_op 0
		.amdhsa_exception_fp_denorm_src 0
		.amdhsa_exception_fp_ieee_div_zero 0
		.amdhsa_exception_fp_ieee_overflow 0
		.amdhsa_exception_fp_ieee_underflow 0
		.amdhsa_exception_fp_ieee_inexact 0
		.amdhsa_exception_int_div_zero 0
	.end_amdhsa_kernel

amdhsa.kernels:
  - .agpr_count:     0
    .args:
      - .offset:         0
        .size:           144
        .value_kind:     by_value
      - .offset:         144
        .size:           4
        .value_kind:     hidden_block_count_x
      - .offset:         148
        .size:           4
        .value_kind:     hidden_block_count_y
      - .offset:         152
        .size:           4
        .value_kind:     hidden_block_count_z
      - .offset:         156
        .size:           2
        .value_kind:     hidden_group_size_x
      - .offset:         158
        .size:           2
        .value_kind:     hidden_group_size_y
      - .offset:         160
        .size:           2
        .value_kind:     hidden_group_size_z
      - .offset:         162
        .size:           2
        .value_kind:     hidden_remainder_x
      - .offset:         164
        .size:           2
        .value_kind:     hidden_remainder_y
      - .offset:         166
        .size:           2
        .value_kind:     hidden_remainder_z
      - .offset:         184
        .size:           8
        .value_kind:     hidden_global_offset_x
      - .offset:         192
        .size:           8
        .value_kind:     hidden_global_offset_y
      - .offset:         200
        .size:           8
        .value_kind:     hidden_global_offset_z
      - .offset:         208
        .size:           2
        .value_kind:     hidden_grid_dims
      - .offset:         232
        .size:           8
        .value_kind:     hidden_multigrid_sync_arg
      - .offset:         264
        .size:           4
        .value_kind:     hidden_dynamic_lds_size
    .group_segment_fixed_size: 0
    .kernarg_segment_align: 8
    .kernarg_segment_size: 400
    .language:       OpenCL C
    .language_version:
      - 2
      - 0
    .max_flat_workgroup_size: 512
    .name:           _Z8mega_fwd4Args
    .private_segment_fixed_size: 0
    .sgpr_count:     108
    .sgpr_spill_count: 222
    .symbol:         _Z8mega_fwd4Args.kd
    .uniform_work_group_size: 1
    .uses_dynamic_stack: false
    .vgpr_count:     256
    .vgpr_spill_count: 0
    .wavefront_size: 64
